# rwkv scan wave: 7 of 8 output-row store addresses derived from the first with one v_lshl_add_u64 and per-phase SGPR +-d*1024 constants (was 8 VALU each), on top of ret_out epilogue hoist
# speedup vs baseline: 1.0032x; 1.0032x over previous
; #define LAS __attribute__((address_space(3)))
; #define LDS_WAIT() asm volatile("s_waitcnt lgkmcnt(0)" ::: "memory")
; __device__ __forceinline__ void phase_rwkv_fused(const Frame& F, const Args& a, int l) {
;     if (F.bid >= 160) return;
;     const int sc = F.bid, seq = sc >> 4, h = (sc >> 1) & 7, z = sc & 1;
;     constexpr int NCH = SEQ / 16, FR_RING = 6 * 15360, FR_FLAGS = FR_RING + 3 * RW_PBB;
;     LAS unsigned char* ring = F.lds + RING_OFF + FR_RING;
;     volatile LAS unsigned* ready = (volatile LAS unsigned*)(F.lds + RING_OFF + FR_FLAGS);
;     volatile LAS unsigned* done = ready + 4;
;     bf16* YS = (bf16*)(F.ws + WS_AR + AR_YSB);
;     __syncthreads();
;     if (F.tid < 16) ready[F.tid] = 0u;
;     __syncthreads();
;     if (F.wave >= 2) {
;     ...
;     const int L = F.lane, li = L & 31, hh = L >> 5, vt = F.wave;
;     f32x16 st[2];
; #pragma unroll
;     for (int kt = 0; kt < 2; ++kt)
; #pragma unroll
;         for (int e = 0; e < 16; ++e) st[kt][e] = 0.f;
;     for (int cl = 0; cl < NCH; ++cl) {
;         const int slot = cl % 3;
;         { unsigned sp = 0; while (ready[slot] != (unsigned)(cl + 1) && ++sp < (1u << 22)) __builtin_amdgcn_s_sleep(1); }
;         asm volatile("" ::: "memory");
;         const LAS unsigned char* rec = ring + slot * RW_PBB;
;         bf16x8 a1[4], btf[2], ktf[2]; f32x4 gm[2][4];
; #pragma unroll
;         for (int ks = 0; ks < 4; ++ks) a1[ks] = *(const LAS bf16x8*)(rec + ks * 1024 + 16 * L);
;         const bf16x8 a2 = *(const LAS bf16x8*)(rec + 4096 + 16 * L), mbr = *(const LAS bf16x8*)(rec + 9216 + 16 * L), vc = *(const LAS bf16x8*)(rec + 10240 + vt * 1024 + 16 * L);
; #pragma unroll
;         for (int kt = 0; kt < 2; ++kt) { btf[kt] = *(const LAS bf16x8*)(rec + 5120 + kt * 1024 + 16 * L); ktf[kt] = *(const LAS bf16x8*)(rec + 7168 + kt * 1024 + 16 * L);
; #pragma unroll
;             for (int q4 = 0; q4 < 4; ++q4) gm[kt][q4] = *(const LAS f32x4*)(rec + 12288 + 4 * (32 * kt + 8 * q4 + 4 * hh)); }
;         LDS_WAIT(); asm volatile("" ::: "memory");
;         if (L == 0) done[slot * 2 + vt] = (unsigned)(cl + 1);
;         f32x16 acc;
; #pragma unroll
;         for (int e = 0; e < 16; ++e) acc[e] = 0.f;
;         acc = MFMA32(a2, vc, acc);
; #pragma unroll
;         for (int ks = 0; ks < 4; ++ks) { const int kt = ks >> 1, b8 = 8 * (ks & 1);
.LBB0_612:
	s_cmp_ge_i32 s50, s74
	s_cselect_b64 s[46:47], -1, 0
	s_and_b64 s[4:5], s[46:47], s[44:45]
	s_andn2_b64 vcc, exec, s[4:5]
	s_cbranch_vccnz .LBB0_781
	v_readlane_b32 s4, v254, 5
	s_mov_b32 s52, 0
	v_mbcnt_lo_u32_b32 v0, -1, 0
	v_mbcnt_hi_u32_b32 v0, -1, v0
	v_readlane_b32 s6, v254, 1
	v_readlane_b32 s5, v254, 10
	v_add_u32_e32 v148, s4, v0
	v_readlane_b32 s7, v254, 2
	v_readfirstlane_b32 s4, v148
	s_ashr_i32 s58, s4, 6
	v_readlane_b32 s4, v254, 0
	s_load_dwordx2 s[50:51], s[6:7], 0xf8
	s_waitcnt lgkmcnt(0)
	s_mov_b32 s8, s5
	s_mov_b32 s9, s4
	s_load_dwordx2 s[4:5], s[6:7], 0xf0
	s_waitcnt lgkmcnt(0)
	v_and_b32_e32 v149, 63, v148
	v_writelane_b32 v254, s8, 58
	v_writelane_b32 v254, s9, 60
	s_cmpk_gt_i32 s9, 0x9f
	s_mov_b64 s[4:5], -1
	s_cbranch_scc1 .LBB0_699
	v_cmp_gt_i32_e32 vcc, 16, v148
	s_waitcnt vmcnt(0)
	s_barrier
	s_and_saveexec_b64 s[4:5], vcc
	v_lshl_add_u32 v0, v148, 2, 0
	v_add_u32_e32 v0, 0x1fe00, v0
	ds_write_b32 v0, v185
	s_or_b64 exec, exec, s[4:5]
	v_readlane_b32 s4, v254, 60
	s_ashr_i32 s8, s4, 4
	s_bfe_u32 s15, s4, 0x30001
	s_and_b32 s17, s4, 1
	s_cmp_lt_i32 s58, 2
	s_mov_b64 s[4:5], -1
	s_waitcnt lgkmcnt(0)
	s_barrier
	s_cbranch_scc0 .LBB0_633
	s_lshl_b32 s4, s58, 2
	s_add_i32 s14, s4, 0
	s_add_i32 s14, s14, 0x1fe10
	s_lshl_b32 s16, s58, 10
	s_cmp_eq_u32 s17, 0
	s_cselect_b64 s[6:7], -1, 0
	s_ashr_i32 s9, s8, 31
	s_lshl_b64 s[10:11], s[8:9], 12
	s_mul_i32 s9, s17, 0xa000
	s_add_u32 s10, s10, s9
	s_addc_u32 s11, s11, 0
	s_lshl_b32 s12, s58, 5
	s_ashr_i32 s13, s12, 31
	s_lshl_b32 s9, s15, 7
	s_add_u32 s9, s50, s9
	s_addc_u32 s19, s51, 0
	s_lshl_b64 s[12:13], s[12:13], 1
	v_and_b32_e32 v0, 31, v148
	s_add_u32 s12, s9, s12
	v_lshrrev_b32_e32 v1, 5, v149
	s_addc_u32 s13, s19, s13
	v_lshlrev_b32_e32 v184, 1, v0
	v_lshlrev_b32_e32 v123, 4, v1
	v_lshlrev_b32_e32 v124, 2, v1
	v_lshl_add_u64 v[0:1], s[12:13], 0, v[184:185]
	s_mov_b64 s[12:13], 0x19e00000
	v_lshl_add_u64 v[120:121], v[0:1], 0, s[12:13]
	v_mov_b32_e32 v0, 0
	v_lshlrev_b32_e32 v122, 4, v149
	s_mov_b32 s18, 0
	v_cmp_eq_u32_e64 s[4:5], 0, v149
	v_or_b32_e32 v125, -16, v124
	v_mov_b32_e32 v1, v0
	v_mov_b32_e32 v2, v0
	v_mov_b32_e32 v3, v0
	v_mov_b32_e32 v4, v0
	v_mov_b32_e32 v5, v0
	v_mov_b32_e32 v6, v0
	v_mov_b32_e32 v7, v0
	v_mov_b32_e32 v8, v0
	v_mov_b32_e32 v9, v0
	v_mov_b32_e32 v10, v0
	v_mov_b32_e32 v11, v0
	v_mov_b32_e32 v12, v0
	v_mov_b32_e32 v13, v0
	v_mov_b32_e32 v14, v0
	v_mov_b32_e32 v15, v0
	v_mov_b32_e32 v16, v0
	v_mov_b32_e32 v17, v0
	v_mov_b32_e32 v18, v0
	v_mov_b32_e32 v19, v0
	v_mov_b32_e32 v20, v0
	v_mov_b32_e32 v21, v0
	v_mov_b32_e32 v22, v0
	v_mov_b32_e32 v23, v0
	v_mov_b32_e32 v24, v0
	v_mov_b32_e32 v25, v0
	v_mov_b32_e32 v26, v0
	v_mov_b32_e32 v27, v0
	v_mov_b32_e32 v28, v0
	v_mov_b32_e32 v29, v0
	v_mov_b32_e32 v30, v0
	v_mov_b32_e32 v31, v0
	s_cmp_eq_u32 s17, 0
	s_cselect_b32 s64, 1, -1
	s_mul_i32 s24, s64, 0x400
	s_ashr_i32 s25, s24, 31
	s_mul_i32 s28, s64, 0x800
	s_ashr_i32 s29, s28, 31
	s_mul_i32 s30, s64, 0xc00
	s_ashr_i32 s31, s30, 31
	s_mul_i32 s44, s64, 0x2000
	s_ashr_i32 s45, s44, 31
	s_mul_i32 s60, s64, 0x2400
	s_ashr_i32 s61, s60, 31
	s_mul_i32 s62, s64, 0x2800
	s_ashr_i32 s63, s62, 31
	s_mul_i32 s70, s64, 0x2c00
	s_ashr_i32 s71, s70, 31
	s_branch .LBB0_619
.LBB0_618:
	s_or_b64 exec, exec, s[12:13]
	s_waitcnt lgkmcnt(12)
	v_mfma_f32_32x32x16_bf16 v[32:47], v[32:35], v[64:67], 0
	v_cvt_pk_bf16_f32 v126, v16, v17
	v_cvt_pk_bf16_f32 v127, v18, v19
	v_cvt_pk_bf16_f32 v128, v20, v21
	v_cvt_pk_bf16_f32 v129, v22, v23
	s_lshl_b32 s12, s18, 4
	s_cmpk_eq_i32 s9, 0x100
	s_mov_b32 s18, s9
	v_mfma_f32_32x32x16_bf16 v[32:47], v[116:119], v[126:129], v[32:47]
	v_cvt_pk_bf16_f32 v116, v24, v25
	v_cvt_pk_bf16_f32 v117, v26, v27
	v_cvt_pk_bf16_f32 v118, v28, v29
	v_cvt_pk_bf16_f32 v119, v30, v31
	s_nop 1
	v_mfma_f32_32x32x16_bf16 v[32:47], v[112:115], v[116:119], v[32:47]
	v_cvt_pk_bf16_f32 v112, v0, v1
	v_cvt_pk_bf16_f32 v113, v2, v3
	v_cvt_pk_bf16_f32 v114, v4, v5
	v_cvt_pk_bf16_f32 v115, v6, v7
	s_nop 1
	v_mfma_f32_32x32x16_bf16 v[32:47], v[108:111], v[112:115], v[32:47]
	v_cvt_pk_bf16_f32 v108, v8, v9
	v_cvt_pk_bf16_f32 v109, v10, v11
	v_cvt_pk_bf16_f32 v110, v12, v13
	v_cvt_pk_bf16_f32 v111, v14, v15
	s_nop 1
	v_mfma_f32_32x32x16_bf16 v[32:47], v[100:103], v[108:111], v[32:47]
	s_nop 11
	v_cvt_pk_bf16_f32 v100, v32, v33
	v_cvt_pk_bf16_f32 v101, v34, v35
	v_cvt_pk_bf16_f32 v102, v36, v37
	v_cvt_pk_bf16_f32 v103, v38, v39
	s_waitcnt lgkmcnt(7)
	s_nop 0
	v_mfma_f32_32x32x16_bf16 v[0:15], v[88:91], v[100:103], v[0:15]
	s_waitcnt lgkmcnt(5)
	v_mfma_f32_32x32x16_bf16 v[0:15], v[80:83], v[64:67], v[0:15]
	v_mfma_f32_32x32x16_bf16 v[32:47], v[48:51], v[100:103], v[32:47]
	s_waitcnt lgkmcnt(3)
	s_nop 9
	v_mul_f32_e64 v0, v52, v0
	v_mul_f32_e64 v1, v53, v1
	v_or_b32_e32 v52, s12, v124
	v_sub_u32_e32 v53, 0xfff, v52
	v_cndmask_b32_e64 v52, v53, v52, s[6:7]
	v_ashrrev_i32_e32 v53, 31, v52
	v_lshl_add_u64 v[32:33], s[10:11], 0, v[52:53]
	v_lshlrev_b64 v[32:33], 10, v[32:33]
	v_pk_mul_f32 v[2:3], v[54:55], v[2:3]
	v_add_u32_e32 v54, s12, v125
	v_cvt_pk_bf16_f32 v34, v40, s0
	v_lshl_add_u64 v[132:133], v[120:121], 0, v[32:33]
	global_store_short v[132:133], v34, off
	v_cvt_pk_bf16_f32 v34, v41, s0
	v_lshl_add_u64 v[32:33], v[132:133], 0, s[24:25]
	global_store_short v[32:33], v34, off
	v_cvt_pk_bf16_f32 v34, v42, s0
	v_lshl_add_u64 v[32:33], v[132:133], 0, s[28:29]
	global_store_short v[32:33], v34, off
	v_cvt_pk_bf16_f32 v34, v43, s0
	v_lshl_add_u64 v[32:33], v[132:133], 0, s[30:31]
	global_store_short v[32:33], v34, off
	v_cvt_pk_bf16_f32 v34, v44, s0
	v_lshl_add_u64 v[32:33], v[132:133], 0, s[44:45]
	global_store_short v[32:33], v34, off
	v_mfma_f32_32x32x16_bf16 v[16:31], v[96:99], v[100:103], v[16:31]
	v_cvt_pk_bf16_f32 v34, v45, s0
	v_lshl_add_u64 v[32:33], v[132:133], 0, s[60:61]
	global_store_short v[32:33], v34, off
	v_mfma_f32_32x32x16_bf16 v[16:31], v[104:107], v[64:67], v[16:31]
	v_cvt_pk_bf16_f32 v34, v46, s0
	v_lshl_add_u64 v[32:33], v[132:133], 0, s[62:63]
	global_store_short v[32:33], v34, off
	s_nop 0
	s_nop 9
	v_pk_mul_f32 v[30:31], v[94:95], v[30:31]
	v_pk_mul_f32 v[28:29], v[92:93], v[28:29]
	v_pk_mul_f32 v[26:27], v[86:87], v[26:27]
	v_pk_mul_f32 v[24:25], v[84:85], v[24:25]
	v_pk_mul_f32 v[22:23], v[78:79], v[22:23]
	v_pk_mul_f32 v[20:21], v[76:77], v[20:21]
	v_pk_mul_f32 v[18:19], v[70:71], v[18:19]
	v_pk_mul_f32 v[16:17], v[68:69], v[16:17]
	s_waitcnt lgkmcnt(0)
	v_pk_mul_f32 v[14:15], v[74:75], v[14:15]
	v_pk_mul_f32 v[12:13], v[72:73], v[12:13]
	v_pk_mul_f32 v[10:11], v[62:63], v[10:11]
	v_pk_mul_f32 v[8:9], v[60:61], v[8:9]
	v_pk_mul_f32 v[6:7], v[58:59], v[6:7]
	v_pk_mul_f32 v[4:5], v[56:57], v[4:5]
	v_cvt_pk_bf16_f32 v34, v47, s0
	v_lshl_add_u64 v[32:33], v[132:133], 0, s[70:71]
	global_store_short v[32:33], v34, off
	s_cbranch_scc1 .LBB0_632
